# c32 + P16 first half-tile base loads widened (12 dwordx2 -> 6 dwordx4 with inverse lane-group exchange after the wait)
# speedup vs baseline: 1.0209x; 1.0029x over previous
; __device__ __forceinline__ unsigned cvt_pk_bf16(float lo, float hi) { unsigned r; asm volatile("v_cvt_pk_bf16_f32 %0, %1, %2" : "=v"(r) : "v"(lo), "v"(hi)); return r; }
;     __device__ __forceinline__ void operator()(const f32x4 (&acc)[2][2][4][2], const Unit& u, int wr, int wc, int fr, int fq) const {
;     ...
;         for (int ai = 0; ai < 2; ++ai) {
;             f32x4 bv[4][2][2]; unsigned long long bw[4][2][2];
; #pragma unroll
;             for (int m = 0; m < 4; ++m) { const size_t off = (size_t)(row0 + ai * HALF + m * 16) * 1024 + col0;
; #pragma unroll
;                 for (int bj = 0; bj < 2; ++bj)
; #pragma unroll
;                     for (int n = 0; n < 2; ++n) {
;                         if (BASE_BF16) bw[m][bj][n] = __builtin_nontemporal_load((const unsigned long long*)((const bf16_t*)base + off + bj * HALF + 16 * n));
;                         else bv[m][bj][n] = __builtin_nontemporal_load((const f32x4*)((const float*)base + off + bj * HALF + 16 * n)); } }
;             asm volatile("" ::: "memory");
; #pragma unroll
;             for (int m = 0; m < 4; ++m) { const size_t off = (size_t)(row0 + ai * HALF + m * 16) * 1024 + col0;
; #pragma unroll
;                 for (int bj = 0; bj < 2; ++bj)
; #pragma unroll
;                     for (int n = 0; n < 2; ++n) {
;                         f32x4 b4;
;                         if (BASE_BF16) { const unsigned long long w = bw[m][bj][n];
;                             b4 = (f32x4){__uint_as_float((unsigned)(w & 0xffffull) << 16), __uint_as_float((unsigned)((w >> 16) & 0xffffull) << 16),
;                                          __uint_as_float((unsigned)((w >> 32) & 0xffffull) << 16), __uint_as_float((unsigned)((w >> 48) & 0xffffull) << 16)}; }
;                         else b4 = bv[m][bj][n];
;                         const f32x4 o = b4 + gv[bj][n] * acc[ai][bj][m][n];
;                         if (OUT_BF16) *(unsigned long long*)((bf16_t*)out + off + bj * HALF + 16 * n) = (unsigned long long)cvt_pk_bf16(o[0], o[1]) | ((unsigned long long)cvt_pk_bf16(o[2], o[3]) << 32);
;                         else *(f32x4*)((float*)out + off + bj * HALF + 16 * n) = o; } }
.LBB0_1483:
	v_lshl_or_b32 v128, s28, 8, v166
	v_lshl_add_u32 v160, s3, 8, v164
	v_ashrrev_i32_e32 v129, 31, v128
	v_ashrrev_i32_e32 v161, 31, v160
	v_or_b32_e32 v178, 16, v160
	v_lshl_add_u64 v[158:159], v[128:129], 1, s[8:9]
	v_lshlrev_b64 v[130:131], 11, v[160:161]
	s_lshr_b32 s3, s3, 4
	v_ashrrev_i32_e32 v179, 31, v178
	v_lshl_add_u64 v[130:131], v[158:159], 0, v[130:131]
	s_mul_i32 s16, s3, 0x1800
	v_lshlrev_b64 v[156:157], 2, v[128:129]
	v_lshlrev_b64 v[128:129], 11, v[178:179]
	v_and_b32_e32 v250, 48, v254
	v_mov_b32_e32 v251, 0
	v_lshrrev_b32_e32 v250, 1, v250
	v_lshl_add_u64 v[252:253], v[130:131], 0, v[250:251]
	global_load_dwordx4 v[170:173], v[252:253], off nt
	v_lshl_add_u64 v[252:253], v[130:131], 0, v[250:251]
	global_load_dwordx4 v[174:177], v[252:253], off offset:256 nt
	s_ashr_i32 s17, s16, 31
	v_lshl_add_u64 v[162:163], v[158:159], 0, v[128:129]
	v_lshl_add_u64 v[252:253], v[162:163], 0, v[250:251]
	global_load_dwordx4 v[180:183], v[252:253], off nt
	s_lshl_b64 s[16:17], s[16:17], 2
	s_add_u32 s16, s41, s16
	s_addc_u32 s17, s42, s17
	v_lshl_add_u64 v[128:129], s[16:17], 0, v[156:157]
	global_load_dwordx4 v[140:143], v[128:129], off
	global_load_dwordx4 v[136:139], v[128:129], off offset:64
	global_load_dwordx4 v[132:135], v[128:129], off offset:512
	s_nop 0
	global_load_dwordx4 v[128:131], v[128:129], off offset:576
	s_nop 0
	v_lshl_add_u64 v[252:253], v[162:163], 0, v[250:251]
	global_load_dwordx4 v[184:187], v[252:253], off offset:256 nt
	v_or_b32_e32 v188, 32, v160
	v_ashrrev_i32_e32 v189, 31, v188
	v_lshlrev_b64 v[192:193], 11, v[188:189]
	v_lshl_add_u64 v[192:193], v[158:159], 0, v[192:193]
	v_lshl_add_u64 v[252:253], v[192:193], 0, v[250:251]
	global_load_dwordx4 v[196:199], v[252:253], off nt
	v_or_b32_e32 v162, 48, v160
	v_ashrrev_i32_e32 v163, 31, v162
	v_lshlrev_b64 v[194:195], 11, v[162:163]
	v_lshl_add_u64 v[194:195], v[158:159], 0, v[194:195]
	global_load_dwordx2 v[200:201], v[192:193], off offset:256 nt
	s_nop 0
	global_load_dwordx2 v[192:193], v[192:193], off offset:288 nt
	s_nop 0
	v_lshl_add_u64 v[252:253], v[194:195], 0, v[250:251]
	global_load_dwordx4 v[202:205], v[252:253], off nt
	global_load_dwordx2 v[206:207], v[194:195], off offset:256 nt
	s_nop 0
	global_load_dwordx2 v[194:195], v[194:195], off offset:288 nt
	v_lshlrev_b64 v[190:191], 12, v[160:161]
	v_lshl_add_u64 v[190:191], s[50:51], 0, v[190:191]
	v_lshlrev_b64 v[178:179], 12, v[178:179]
	v_lshl_add_u64 v[190:191], v[190:191], 0, v[156:157]
	s_and_b64 vcc, exec, s[0:1]
	s_mov_b64 s[0:1], -1
	s_waitcnt vmcnt(0)
	v_permlane16_swap_b32_e32 v170, v172
	v_permlane16_swap_b32_e32 v171, v173
	v_permlane16_swap_b32_e32 v174, v176
	v_permlane16_swap_b32_e32 v175, v177
	v_permlane16_swap_b32_e32 v180, v182
	v_permlane16_swap_b32_e32 v181, v183
	v_permlane16_swap_b32_e32 v184, v186
	v_permlane16_swap_b32_e32 v185, v187
	v_permlane16_swap_b32_e32 v196, v198
	v_permlane16_swap_b32_e32 v197, v199
	v_permlane16_swap_b32_e32 v202, v204
	v_permlane16_swap_b32_e32 v203, v205
	v_permlane32_swap_b32_e32 v170, v172
	v_permlane32_swap_b32_e32 v171, v173
	v_permlane32_swap_b32_e32 v174, v176
	v_permlane32_swap_b32_e32 v175, v177
	v_permlane32_swap_b32_e32 v180, v182
	v_permlane32_swap_b32_e32 v181, v183
	v_permlane32_swap_b32_e32 v184, v186
	v_permlane32_swap_b32_e32 v185, v187
	v_permlane32_swap_b32_e32 v196, v198
	v_permlane32_swap_b32_e32 v197, v199
	v_permlane32_swap_b32_e32 v202, v204
	v_permlane32_swap_b32_e32 v203, v205
	s_nop 1
	v_alignbit_b32 v161, v171, v170, 16
	v_lshlrev_b32_e32 v208, 16, v170
	v_and_b32_e32 v209, 0xffff0000, v170
	v_and_b32_e32 v171, 0xffff0000, v171
	v_lshlrev_b32_e32 v210, 16, v172
	v_and_b32_e32 v211, 0xffff0000, v172
	v_alignbit_b32 v172, v173, v172, 16
	v_lshlrev_b32_e32 v212, 16, v174
	v_and_b32_e32 v213, 0xffff0000, v174
	v_alignbit_b32 v174, v175, v174, 16
	v_lshlrev_b32_e32 v214, 16, v176
	v_and_b32_e32 v215, 0xffff0000, v176
	v_alignbit_b32 v176, v177, v176, 16
	v_and_b32_e32 v170, 0xffff0000, v161
	v_and_b32_e32 v173, 0xffff0000, v173
	v_and_b32_e32 v175, 0xffff0000, v175
	v_and_b32_e32 v177, 0xffff0000, v177
	v_and_b32_e32 v172, 0xffff0000, v172
	v_and_b32_e32 v174, 0xffff0000, v174
	v_and_b32_e32 v176, 0xffff0000, v176
	v_alignbit_b32 v161, v181, v180, 16
	v_pk_fma_f32 v[124:125], v[124:125], v[140:141], v[208:209]
	v_pk_fma_f32 v[126:127], v[126:127], v[142:143], v[170:171]
	v_pk_fma_f32 v[112:113], v[112:113], v[132:133], v[212:213]
	v_lshlrev_b32_e32 v216, 16, v180
	v_and_b32_e32 v217, 0xffff0000, v180
	v_and_b32_e32 v181, 0xffff0000, v181
	v_and_b32_e32 v180, 0xffff0000, v161
	v_pk_fma_f32 v[120:121], v[120:121], v[136:137], v[210:211]
	v_pk_fma_f32 v[122:123], v[122:123], v[138:139], v[172:173]
	v_pk_fma_f32 v[114:115], v[114:115], v[134:135], v[174:175]
	v_pk_fma_f32 v[108:109], v[108:109], v[128:129], v[214:215]
	v_pk_fma_f32 v[110:111], v[110:111], v[130:131], v[176:177]
	global_store_dwordx4 v[190:191], v[124:127], off
	global_store_dwordx4 v[190:191], v[120:123], off offset:64
	global_store_dwordx4 v[190:191], v[112:115], off offset:512
	global_store_dwordx4 v[190:191], v[108:111], off offset:576
	s_nop 0
	v_lshl_add_u64 v[112:113], s[50:51], 0, v[178:179]
	v_pk_fma_f32 v[108:109], v[116:117], v[140:141], v[216:217]
	v_pk_fma_f32 v[110:111], v[118:119], v[142:143], v[180:181]
	v_lshl_add_u64 v[112:113], v[112:113], 0, v[156:157]
	global_store_dwordx4 v[112:113], v[108:111], off
	s_nop 1
	v_alignbit_b32 v110, v183, v182, 16
	v_lshlrev_b32_e32 v108, 16, v182
	v_and_b32_e32 v109, 0xffff0000, v182
	v_and_b32_e32 v110, 0xffff0000, v110
	v_and_b32_e32 v111, 0xffff0000, v183
	v_pk_fma_f32 v[104:105], v[104:105], v[136:137], v[108:109]
; __device__ __forceinline__ unsigned cvt_pk_bf16(float lo, float hi) { unsigned r; asm volatile("v_cvt_pk_bf16_f32 %0, %1, %2" : "=v"(r) : "v"(lo), "v"(hi)); return r; }
;     __device__ __forceinline__ void operator()(const f32x4 (&acc)[2][2][4][2], const Unit& u, int wr, int wc, int fr, int fq) const {
;     ...
;         for (int ai = 0; ai < 2; ++ai) {
;             f32x4 bv[4][2][2]; unsigned long long bw[4][2][2];
; #pragma unroll
;             for (int m = 0; m < 4; ++m) { const size_t off = (size_t)(row0 + ai * HALF + m * 16) * 1024 + col0;
; #pragma unroll
;                 for (int bj = 0; bj < 2; ++bj)
; #pragma unroll
;                     for (int n = 0; n < 2; ++n) {
;                         if (BASE_BF16) bw[m][bj][n] = __builtin_nontemporal_load((const unsigned long long*)((const bf16_t*)base + off + bj * HALF + 16 * n));
;                         else bv[m][bj][n] = __builtin_nontemporal_load((const f32x4*)((const float*)base + off + bj * HALF + 16 * n)); } }
;             asm volatile("" ::: "memory");
; #pragma unroll
;             for (int m = 0; m < 4; ++m) { const size_t off = (size_t)(row0 + ai * HALF + m * 16) * 1024 + col0;
; #pragma unroll
;                 for (int bj = 0; bj < 2; ++bj)
; #pragma unroll
;                     for (int n = 0; n < 2; ++n) {
;                         f32x4 b4;
;                         if (BASE_BF16) { const unsigned long long w = bw[m][bj][n];
;                             b4 = (f32x4){__uint_as_float((unsigned)(w & 0xffffull) << 16), __uint_as_float((unsigned)((w >> 16) & 0xffffull) << 16),
;                                          __uint_as_float((unsigned)((w >> 32) & 0xffffull) << 16), __uint_as_float((unsigned)((w >> 48) & 0xffffull) << 16)}; }
;                         else b4 = bv[m][bj][n];
;                         const f32x4 o = b4 + gv[bj][n] * acc[ai][bj][m][n];
;                         if (OUT_BF16) *(unsigned long long*)((bf16_t*)out + off + bj * HALF + 16 * n) = (unsigned long long)cvt_pk_bf16(o[0], o[1]) | ((unsigned long long)cvt_pk_bf16(o[2], o[3]) << 32);
;                         else *(f32x4*)((float*)out + off + bj * HALF + 16 * n) = o; } }
	v_pk_fma_f32 v[106:107], v[106:107], v[138:139], v[110:111]
	global_store_dwordx4 v[112:113], v[104:107], off offset:64
	s_nop 1
	v_alignbit_b32 v106, v185, v184, 16
	v_lshlrev_b32_e32 v104, 16, v184
	v_and_b32_e32 v105, 0xffff0000, v184
	v_and_b32_e32 v106, 0xffff0000, v106
	v_and_b32_e32 v107, 0xffff0000, v185
	v_pk_fma_f32 v[100:101], v[100:101], v[132:133], v[104:105]
	v_pk_fma_f32 v[102:103], v[102:103], v[134:135], v[106:107]
	global_store_dwordx4 v[112:113], v[100:103], off offset:512
	s_nop 1
	v_alignbit_b32 v102, v187, v186, 16
	v_lshlrev_b32_e32 v100, 16, v186
	v_and_b32_e32 v101, 0xffff0000, v186
	v_and_b32_e32 v102, 0xffff0000, v102
	v_and_b32_e32 v103, 0xffff0000, v187
	v_pk_fma_f32 v[92:93], v[92:93], v[128:129], v[100:101]
	v_pk_fma_f32 v[94:95], v[94:95], v[130:131], v[102:103]
	global_store_dwordx4 v[112:113], v[92:95], off offset:576
	v_lshlrev_b64 v[100:101], 12, v[188:189]
	s_nop 0
	v_lshlrev_b32_e32 v92, 16, v196
	v_and_b32_e32 v93, 0xffff0000, v196
	v_alignbit_b32 v94, v197, v196, 16
	v_and_b32_e32 v94, 0xffff0000, v94
	v_and_b32_e32 v95, 0xffff0000, v197
	v_pk_fma_f32 v[92:93], v[96:97], v[140:141], v[92:93]
	v_lshl_add_u64 v[96:97], s[50:51], 0, v[100:101]
	v_pk_fma_f32 v[94:95], v[98:99], v[142:143], v[94:95]
	v_lshl_add_u64 v[96:97], v[96:97], 0, v[156:157]
	global_store_dwordx4 v[96:97], v[92:95], off
	v_add_u32_e32 v98, 0xb0, v160
	v_ashrrev_i32_e32 v99, 31, v98
	v_alignbit_b32 v94, v199, v198, 16
	v_lshlrev_b32_e32 v92, 16, v198
	v_and_b32_e32 v93, 0xffff0000, v198
	v_and_b32_e32 v94, 0xffff0000, v94
	v_and_b32_e32 v95, 0xffff0000, v199
	v_pk_fma_f32 v[88:89], v[88:89], v[136:137], v[92:93]
	v_pk_fma_f32 v[90:91], v[90:91], v[138:139], v[94:95]
	global_store_dwordx4 v[96:97], v[88:91], off offset:64
	s_nop 1
	v_alignbit_b32 v90, v201, v200, 16
	v_lshlrev_b32_e32 v88, 16, v200
	v_and_b32_e32 v89, 0xffff0000, v200
	v_and_b32_e32 v90, 0xffff0000, v90
	v_and_b32_e32 v91, 0xffff0000, v201
	v_pk_fma_f32 v[84:85], v[84:85], v[132:133], v[88:89]
	v_pk_fma_f32 v[86:87], v[86:87], v[134:135], v[90:91]
	global_store_dwordx4 v[96:97], v[84:87], off offset:512
	v_add_u32_e32 v88, 0xa0, v160
	v_ashrrev_i32_e32 v89, 31, v88
	v_alignbit_b32 v86, v193, v192, 16
	v_lshlrev_b32_e32 v84, 16, v192
	v_and_b32_e32 v85, 0xffff0000, v192
	v_and_b32_e32 v86, 0xffff0000, v86
	v_and_b32_e32 v87, 0xffff0000, v193
	v_pk_fma_f32 v[76:77], v[76:77], v[128:129], v[84:85]
	v_pk_fma_f32 v[78:79], v[78:79], v[130:131], v[86:87]
	global_store_dwordx4 v[96:97], v[76:79], off offset:576
	v_lshlrev_b64 v[84:85], 12, v[162:163]
	s_nop 0
	v_lshlrev_b32_e32 v76, 16, v202
	v_and_b32_e32 v77, 0xffff0000, v202
	v_alignbit_b32 v78, v203, v202, 16
	v_and_b32_e32 v78, 0xffff0000, v78
	v_and_b32_e32 v79, 0xffff0000, v203
	v_pk_fma_f32 v[76:77], v[80:81], v[140:141], v[76:77]
	v_lshl_add_u64 v[80:81], s[50:51], 0, v[84:85]
	v_pk_fma_f32 v[78:79], v[82:83], v[142:143], v[78:79]
	v_lshl_add_u64 v[80:81], v[80:81], 0, v[156:157]
	global_store_dwordx4 v[80:81], v[76:79], off
	s_nop 1
	v_alignbit_b32 v78, v205, v204, 16
	v_lshlrev_b32_e32 v76, 16, v204
	v_and_b32_e32 v77, 0xffff0000, v204
	v_and_b32_e32 v78, 0xffff0000, v78
	v_and_b32_e32 v79, 0xffff0000, v205
	v_pk_fma_f32 v[72:73], v[72:73], v[136:137], v[76:77]
	v_pk_fma_f32 v[74:75], v[74:75], v[138:139], v[78:79]
	global_store_dwordx4 v[80:81], v[72:75], off offset:64
	v_add_u32_e32 v78, 0x90, v160
	v_ashrrev_i32_e32 v79, 31, v78
	v_alignbit_b32 v74, v207, v206, 16
	v_lshlrev_b32_e32 v72, 16, v206
	v_and_b32_e32 v73, 0xffff0000, v206
	v_and_b32_e32 v74, 0xffff0000, v74
	v_and_b32_e32 v75, 0xffff0000, v207
	v_pk_fma_f32 v[68:69], v[68:69], v[132:133], v[72:73]
	v_pk_fma_f32 v[70:71], v[70:71], v[134:135], v[74:75]
	global_store_dwordx4 v[80:81], v[68:71], off offset:512
	s_nop 1
	v_lshlrev_b32_e32 v68, 16, v194
	v_and_b32_e32 v69, 0xffff0000, v194
	v_alignbit_b32 v70, v195, v194, 16
	v_and_b32_e32 v70, 0xffff0000, v70
	v_and_b32_e32 v71, 0xffff0000, v195
	v_pk_fma_f32 v[64:65], v[64:65], v[128:129], v[68:69]
	v_add_u32_e32 v68, 0x80, v160
	v_pk_fma_f32 v[66:67], v[66:67], v[130:131], v[70:71]
	v_ashrrev_i32_e32 v69, 31, v68
	global_store_dwordx4 v[80:81], v[64:67], off offset:576
	s_nop 1
	v_lshlrev_b64 v[64:65], 11, v[68:69]
	v_lshl_add_u64 v[64:65], v[158:159], 0, v[64:65]
	global_load_dwordx2 v[70:71], v[64:65], off nt
	global_load_dwordx2 v[72:73], v[64:65], off offset:32 nt
	global_load_dwordx2 v[74:75], v[64:65], off offset:256 nt
	global_load_dwordx2 v[76:77], v[64:65], off offset:288 nt
	v_lshlrev_b64 v[64:65], 11, v[78:79]
	v_lshl_add_u64 v[64:65], v[158:159], 0, v[64:65]
	global_load_dwordx2 v[80:81], v[64:65], off nt
	global_load_dwordx2 v[82:83], v[64:65], off offset:32 nt
	global_load_dwordx2 v[84:85], v[64:65], off offset:256 nt
	global_load_dwordx2 v[86:87], v[64:65], off offset:288 nt
	v_lshlrev_b64 v[64:65], 11, v[88:89]
	v_lshl_add_u64 v[64:65], v[158:159], 0, v[64:65]
	global_load_dwordx2 v[90:91], v[64:65], off nt
	global_load_dwordx2 v[92:93], v[64:65], off offset:32 nt
	global_load_dwordx2 v[94:95], v[64:65], off offset:256 nt
	global_load_dwordx2 v[96:97], v[64:65], off offset:288 nt
	v_lshlrev_b64 v[64:65], 11, v[98:99]
	v_lshl_add_u64 v[64:65], v[158:159], 0, v[64:65]
	global_load_dwordx2 v[100:101], v[64:65], off nt
	global_load_dwordx2 v[102:103], v[64:65], off offset:32 nt
	global_load_dwordx2 v[66:67], v[64:65], off offset:256 nt
	s_nop 0
	global_load_dwordx2 v[64:65], v[64:65], off offset:288 nt
	v_lshlrev_b64 v[68:69], 12, v[68:69]
	v_lshl_add_u64 v[68:69], s[50:51], 0, v[68:69]
	v_lshl_add_u64 v[68:69], v[68:69], 0, v[156:157]
	s_waitcnt vmcnt(15)
; __device__ __forceinline__ unsigned cvt_pk_bf16(float lo, float hi) { unsigned r; asm volatile("v_cvt_pk_bf16_f32 %0, %1, %2" : "=v"(r) : "v"(lo), "v"(hi)); return r; }
;     __device__ __forceinline__ void operator()(const f32x4 (&acc)[2][2][4][2], const Unit& u, int wr, int wc, int fr, int fq) const {
;     ...
;             for (int m = 0; m < 4; ++m) { const size_t off = (size_t)(row0 + ai * HALF + m * 16) * 1024 + col0;
; #pragma unroll
;                 for (int bj = 0; bj < 2; ++bj)
; #pragma unroll
;                     for (int n = 0; n < 2; ++n) {
;                         f32x4 b4;
;                         if (BASE_BF16) { const unsigned long long w = bw[m][bj][n];
;                             b4 = (f32x4){__uint_as_float((unsigned)(w & 0xffffull) << 16), __uint_as_float((unsigned)((w >> 16) & 0xffffull) << 16),
;                                          __uint_as_float((unsigned)((w >> 32) & 0xffffull) << 16), __uint_as_float((unsigned)((w >> 48) & 0xffffull) << 16)}; }
;                         else b4 = bv[m][bj][n];
;                         const f32x4 o = b4 + gv[bj][n] * acc[ai][bj][m][n];
;                         if (OUT_BF16) *(unsigned long long*)((bf16_t*)out + off + bj * HALF + 16 * n) = (unsigned long long)cvt_pk_bf16(o[0], o[1]) | ((unsigned long long)cvt_pk_bf16(o[2], o[3]) << 32);
;                         else *(f32x4*)((float*)out + off + bj * HALF + 16 * n) = o; } }
	v_lshlrev_b32_e32 v104, 16, v70
	v_and_b32_e32 v105, 0xffff0000, v70
	v_alignbit_b32 v70, v71, v70, 16
	v_and_b32_e32 v70, 0xffff0000, v70
	v_and_b32_e32 v71, 0xffff0000, v71
	v_pk_fma_f32 v[60:61], v[60:61], v[140:141], v[104:105]
	v_pk_fma_f32 v[62:63], v[62:63], v[142:143], v[70:71]
	global_store_dwordx4 v[68:69], v[60:63], off
	s_waitcnt vmcnt(15)
	s_nop 0
	v_alignbit_b32 v62, v73, v72, 16
	v_lshlrev_b32_e32 v60, 16, v72
	v_and_b32_e32 v61, 0xffff0000, v72
	v_and_b32_e32 v62, 0xffff0000, v62
	v_and_b32_e32 v63, 0xffff0000, v73
	v_pk_fma_f32 v[56:57], v[56:57], v[136:137], v[60:61]
	v_pk_fma_f32 v[58:59], v[58:59], v[138:139], v[62:63]
	global_store_dwordx4 v[68:69], v[56:59], off offset:64
	s_waitcnt vmcnt(15)
	s_nop 0
	v_alignbit_b32 v58, v75, v74, 16
	v_lshlrev_b32_e32 v56, 16, v74
	v_and_b32_e32 v57, 0xffff0000, v74
	v_and_b32_e32 v58, 0xffff0000, v58
	v_and_b32_e32 v59, 0xffff0000, v75
	v_pk_fma_f32 v[52:53], v[52:53], v[132:133], v[56:57]
	v_pk_fma_f32 v[54:55], v[54:55], v[134:135], v[58:59]
	global_store_dwordx4 v[68:69], v[52:55], off offset:512
	s_waitcnt vmcnt(15)
	s_nop 0
	v_alignbit_b32 v54, v77, v76, 16
	v_lshlrev_b32_e32 v52, 16, v76
	v_and_b32_e32 v53, 0xffff0000, v76
	v_and_b32_e32 v54, 0xffff0000, v54
	v_and_b32_e32 v55, 0xffff0000, v77
	v_pk_fma_f32 v[44:45], v[44:45], v[128:129], v[52:53]
	v_pk_fma_f32 v[46:47], v[46:47], v[130:131], v[54:55]
	global_store_dwordx4 v[68:69], v[44:47], off offset:576
	v_lshlrev_b64 v[52:53], 12, v[78:79]
	s_waitcnt vmcnt(15)
	v_lshlrev_b32_e32 v44, 16, v80
	v_and_b32_e32 v45, 0xffff0000, v80
	v_alignbit_b32 v46, v81, v80, 16
	v_and_b32_e32 v46, 0xffff0000, v46
	v_and_b32_e32 v47, 0xffff0000, v81
	v_pk_fma_f32 v[44:45], v[48:49], v[140:141], v[44:45]
	v_lshl_add_u64 v[48:49], s[50:51], 0, v[52:53]
	v_pk_fma_f32 v[46:47], v[50:51], v[142:143], v[46:47]
	v_lshl_add_u64 v[48:49], v[48:49], 0, v[156:157]
	global_store_dwordx4 v[48:49], v[44:47], off
	s_waitcnt vmcnt(15)
	s_nop 0
	v_alignbit_b32 v46, v83, v82, 16
	v_lshlrev_b32_e32 v44, 16, v82
	v_and_b32_e32 v45, 0xffff0000, v82
	v_and_b32_e32 v46, 0xffff0000, v46
	v_and_b32_e32 v47, 0xffff0000, v83
	v_pk_fma_f32 v[40:41], v[40:41], v[136:137], v[44:45]
	v_pk_fma_f32 v[42:43], v[42:43], v[138:139], v[46:47]
	global_store_dwordx4 v[48:49], v[40:43], off offset:64
	s_waitcnt vmcnt(15)
	s_nop 0
	v_alignbit_b32 v42, v85, v84, 16
	v_lshlrev_b32_e32 v40, 16, v84
	v_and_b32_e32 v41, 0xffff0000, v84
	v_and_b32_e32 v42, 0xffff0000, v42
	v_and_b32_e32 v43, 0xffff0000, v85
	v_pk_fma_f32 v[36:37], v[36:37], v[132:133], v[40:41]
	v_pk_fma_f32 v[38:39], v[38:39], v[134:135], v[42:43]
	global_store_dwordx4 v[48:49], v[36:39], off offset:512
	s_waitcnt vmcnt(15)
	s_nop 0
	v_alignbit_b32 v38, v87, v86, 16
	v_lshlrev_b32_e32 v36, 16, v86
	v_and_b32_e32 v37, 0xffff0000, v86
	v_and_b32_e32 v38, 0xffff0000, v38
	v_and_b32_e32 v39, 0xffff0000, v87
	v_pk_fma_f32 v[28:29], v[28:29], v[128:129], v[36:37]
	v_pk_fma_f32 v[30:31], v[30:31], v[130:131], v[38:39]
	global_store_dwordx4 v[48:49], v[28:31], off offset:576
	v_lshlrev_b64 v[36:37], 12, v[88:89]
	s_waitcnt vmcnt(15)
	v_lshlrev_b32_e32 v28, 16, v90
	v_and_b32_e32 v29, 0xffff0000, v90
	v_alignbit_b32 v30, v91, v90, 16
	v_and_b32_e32 v30, 0xffff0000, v30
	v_and_b32_e32 v31, 0xffff0000, v91
	v_pk_fma_f32 v[28:29], v[32:33], v[140:141], v[28:29]
	v_lshl_add_u64 v[32:33], s[50:51], 0, v[36:37]
	v_pk_fma_f32 v[30:31], v[34:35], v[142:143], v[30:31]
	v_lshl_add_u64 v[32:33], v[32:33], 0, v[156:157]
	global_store_dwordx4 v[32:33], v[28:31], off
	s_waitcnt vmcnt(15)
	s_nop 0
	v_alignbit_b32 v30, v93, v92, 16
	v_lshlrev_b32_e32 v28, 16, v92
	v_and_b32_e32 v29, 0xffff0000, v92
	v_and_b32_e32 v30, 0xffff0000, v30
	v_and_b32_e32 v31, 0xffff0000, v93
	v_pk_fma_f32 v[24:25], v[24:25], v[136:137], v[28:29]
	v_pk_fma_f32 v[26:27], v[26:27], v[138:139], v[30:31]
	global_store_dwordx4 v[32:33], v[24:27], off offset:64
	s_waitcnt vmcnt(15)
	s_nop 0
	v_alignbit_b32 v26, v95, v94, 16
	v_lshlrev_b32_e32 v24, 16, v94
	v_and_b32_e32 v25, 0xffff0000, v94
	v_and_b32_e32 v26, 0xffff0000, v26
	v_and_b32_e32 v27, 0xffff0000, v95
	v_pk_fma_f32 v[20:21], v[20:21], v[132:133], v[24:25]
	v_pk_fma_f32 v[22:23], v[22:23], v[134:135], v[26:27]
	global_store_dwordx4 v[32:33], v[20:23], off offset:512
	s_waitcnt vmcnt(15)
	s_nop 0
	v_alignbit_b32 v22, v97, v96, 16
	v_lshlrev_b32_e32 v20, 16, v96
	v_and_b32_e32 v21, 0xffff0000, v96
	v_and_b32_e32 v22, 0xffff0000, v22
	v_and_b32_e32 v23, 0xffff0000, v97
	v_pk_fma_f32 v[12:13], v[12:13], v[128:129], v[20:21]
	v_pk_fma_f32 v[14:15], v[14:15], v[130:131], v[22:23]
	global_store_dwordx4 v[32:33], v[12:15], off offset:576
	v_lshlrev_b64 v[20:21], 12, v[98:99]
	s_waitcnt vmcnt(15)
	v_lshlrev_b32_e32 v12, 16, v100
	v_and_b32_e32 v13, 0xffff0000, v100
	v_alignbit_b32 v14, v101, v100, 16
	v_and_b32_e32 v14, 0xffff0000, v14
	v_and_b32_e32 v15, 0xffff0000, v101
	v_pk_fma_f32 v[12:13], v[16:17], v[140:141], v[12:13]
	v_lshl_add_u64 v[16:17], s[50:51], 0, v[20:21]
	v_pk_fma_f32 v[14:15], v[18:19], v[142:143], v[14:15]
	v_lshl_add_u64 v[16:17], v[16:17], 0, v[156:157]
	global_store_dwordx4 v[16:17], v[12:15], off
	s_waitcnt vmcnt(15)
	s_nop 0
	v_alignbit_b32 v14, v103, v102, 16
	v_lshlrev_b32_e32 v12, 16, v102
	v_and_b32_e32 v13, 0xffff0000, v102
	v_and_b32_e32 v14, 0xffff0000, v14
	v_and_b32_e32 v15, 0xffff0000, v103
	v_pk_fma_f32 v[8:9], v[8:9], v[136:137], v[12:13]
	v_pk_fma_f32 v[10:11], v[10:11], v[138:139], v[14:15]
	global_store_dwordx4 v[16:17], v[8:11], off offset:64
	s_waitcnt vmcnt(15)
	s_nop 0
	v_alignbit_b32 v10, v67, v66, 16
	v_lshlrev_b32_e32 v8, 16, v66
	v_and_b32_e32 v9, 0xffff0000, v66
	v_and_b32_e32 v10, 0xffff0000, v10
	v_and_b32_e32 v11, 0xffff0000, v67
	v_pk_fma_f32 v[4:5], v[4:5], v[132:133], v[8:9]
	v_pk_fma_f32 v[6:7], v[6:7], v[134:135], v[10:11]
	global_store_dwordx4 v[16:17], v[4:7], off offset:512
	s_waitcnt vmcnt(15)
	s_nop 0
	v_alignbit_b32 v6, v65, v64, 16
	v_lshlrev_b32_e32 v4, 16, v64
	v_and_b32_e32 v5, 0xffff0000, v64
	v_and_b32_e32 v6, 0xffff0000, v6
	v_and_b32_e32 v7, 0xffff0000, v65
	v_pk_fma_f32 v[0:1], v[0:1], v[128:129], v[4:5]
	v_pk_fma_f32 v[2:3], v[2:3], v[130:131], v[6:7]
	global_store_dwordx4 v[16:17], v[0:3], off offset:576
	s_cbranch_vccnz .LBB0_1468
	s_andn2_b64 vcc, exec, s[6:7]
	s_cbranch_vccnz .LBB0_1467
	s_barrier
	s_branch .LBB0_1467
